# attention units: static priority 2 for the younger wave half (waves 4-7) instead of the older half
# speedup vs baseline: 1.0014x; 1.0014x over previous
; template <int TYPE>
; __device__ __forceinline__ void attn_mfma_unit2(const AttnCtx& A, unsigned char* ws, LAS unsigned char* lds, int tid, const AUnit& u) {
;     ...
;     if (w < 4) __builtin_amdgcn_s_setprio(2); else __builtin_amdgcn_s_setprio(0);
.LBB0_2774:
	s_mov_b64 s[8:9], -1
	s_mov_b64 s[2:3], 0
	s_cmp_lt_i32 s17, 2
	s_mov_b64 s[6:7], 0
	s_cbranch_scc1 .LBB0_2785
	s_cmp_eq_u32 s17, 2
	s_mov_b64 s[6:7], -1
	s_cbranch_scc0 .LBB0_2801
	v_mbcnt_lo_u32_b32 v2, -1, 0
	v_mbcnt_hi_u32_b32 v2, -1, v2
	s_nop 0
	v_add_u32_e32 v0, s54, v2
	s_nop 0
	v_readfirstlane_b32 s8, v0
	s_ashr_i32 s10, s8, 6
	s_cmp_gt_i32 s10, 3
	s_cbranch_scc0 .LBB0_2778
	s_setprio 2
	s_mov_b64 s[6:7], 0
.LBB0_2778:
	s_andn2_b64 vcc, exec, s[6:7]
	s_cbranch_vccnz .LBB0_2780
	s_setprio 0

; template <int TYPE>
; __device__ __forceinline__ void attn_mfma_unit2(const AttnCtx& A, unsigned char* ws, LAS unsigned char* lds, int tid, const AUnit& u) {
;     ...
;     if (w < 4) __builtin_amdgcn_s_setprio(2); else __builtin_amdgcn_s_setprio(0);
.LBB0_2803:
	v_mbcnt_lo_u32_b32 v2, -1, 0
	v_mbcnt_hi_u32_b32 v2, -1, v2
	s_mov_b64 s[2:3], -1
	v_add_u32_e32 v5, s54, v2
	s_nop 0
	v_readfirstlane_b32 s12, v5
	s_ashr_i32 s11, s12, 6
	s_cmp_gt_i32 s11, 3
	s_cbranch_scc0 .LBB0_2805
	s_setprio 2
	s_mov_b64 s[2:3], 0
.LBB0_2805:
	s_andn2_b64 vcc, exec, s[2:3]
	s_cbranch_vccnz .LBB0_2807
	s_setprio 0

; template <int TYPE>
; __device__ __forceinline__ void attn_mfma_unit2(const AttnCtx& A, unsigned char* ws, LAS unsigned char* lds, int tid, const AUnit& u) {
;     ...
;     if (w < 4) __builtin_amdgcn_s_setprio(2); else __builtin_amdgcn_s_setprio(0);
.LBB0_2897:
	v_mbcnt_lo_u32_b32 v2, -1, 0
	v_mbcnt_hi_u32_b32 v2, -1, v2
	s_mov_b64 s[2:3], -1
	v_add_u32_e32 v0, s54, v2
	s_nop 0
	v_readfirstlane_b32 s11, v0
	s_ashr_i32 s12, s11, 6
	s_cmp_gt_i32 s12, 3
	s_cbranch_scc0 .LBB0_2899
	s_setprio 2
	s_mov_b64 s[2:3], 0
